# cand30 + prompt attention first-block units: the four masked K/V row-group loads issued together (own registers), one wait, then the LDS writes
# speedup vs baseline: 1.0044x; 1.0044x over previous
.LBB0_1408:
	s_cbranch_execz .LBB0_1401
	s_add_u32 s48, s48, 0xffffff80
	s_addc_u32 s49, s49, -1
	s_lshl_b32 s59, s58, 6
	v_mov_b32_e32 v12, 0
	v_mov_b32_e32 v13, 0
	v_mov_b32_e32 v14, 0
	v_mov_b32_e32 v15, 0
	v_mov_b32_e32 v8, 0
	v_mov_b32_e32 v9, 0
	v_mov_b32_e32 v10, 0
	v_mov_b32_e32 v11, 0
	v_mov_b32_e32 v6, 0
	s_and_saveexec_b64 s[50:51], s[18:19]
	s_cbranch_execz .LBB0_1411
	v_lshl_add_u64 v[2:3], s[48:49], 0, v[66:67]
	v_mov_b64_e32 v[8:9], s[26:27]
	v_mad_u64_u32 v[8:9], s[60:61], v2, s53, v[8:9]
	v_mad_i32_i24 v9, v3, s53, v9
	s_lshl_b32 s28, s59, 1
	v_lshl_add_u64 v[2:3], v[8:9], 0, s[28:29]
	v_mov_b32_e32 v83, v4
	v_lshl_add_u64 v[2:3], v[2:3], 0, v[82:83]
	v_lshl_add_u64 v[8:9], v[2:3], 0, s[30:31]
	v_add_co_u32_e32 v2, vcc, 0x2000, v2
	s_nop 1
	v_addc_co_u32_e32 v3, vcc, 0, v3, vcc
	global_load_dwordx4 v[12:15], v[2:3], off
	s_nop 0
	global_load_dwordx4 v[8:11], v[8:9], off offset:1024
.LBB0_1411:
	s_or_b64 exec, exec, s[50:51]
	v_mov_b32_e32 v36, 0
	v_mov_b32_e32 v37, 0
	v_mov_b32_e32 v38, 0
	v_mov_b32_e32 v39, 0
	v_mov_b32_e32 v32, 0
	v_mov_b32_e32 v33, 0
	v_mov_b32_e32 v34, 0
	v_mov_b32_e32 v35, 0
	s_and_saveexec_b64 s[50:51], s[20:21]
	s_cbranch_execz .LBB0_1413
	v_lshl_add_u64 v[2:3], s[48:49], 0, v[68:69]
	v_mov_b64_e32 v[32:33], s[26:27]
	v_mad_u64_u32 v[32:33], s[60:61], v2, s53, v[32:33]
	v_mad_i32_i24 v33, v3, s53, v33
	s_lshl_b32 s28, s59, 1
	v_lshl_add_u64 v[2:3], v[32:33], 0, s[28:29]
	v_mov_b32_e32 v83, v4
	v_lshl_add_u64 v[2:3], v[2:3], 0, v[82:83]
	v_lshl_add_u64 v[32:33], v[2:3], 0, s[30:31]
	v_add_co_u32_e32 v2, vcc, 0x2000, v2
	s_nop 1
	v_addc_co_u32_e32 v3, vcc, 0, v3, vcc
	global_load_dwordx4 v[36:39], v[2:3], off
	s_nop 0
	global_load_dwordx4 v[32:35], v[32:33], off offset:1024
.LBB0_1413:
	s_or_b64 exec, exec, s[50:51]
	v_mov_b32_e32 v194, 0
	v_mov_b32_e32 v195, 0
	v_mov_b32_e32 v196, 0
	v_mov_b32_e32 v197, 0
	v_mov_b32_e32 v190, 0
	v_mov_b32_e32 v191, 0
	v_mov_b32_e32 v192, 0
	v_mov_b32_e32 v193, 0
	v_mov_b32_e32 v188, 0
	s_and_saveexec_b64 s[50:51], s[22:23]
	s_cbranch_execz .LBB0_1415
	v_lshl_add_u64 v[2:3], s[48:49], 0, v[70:71]
	v_mov_b64_e32 v[190:191], s[26:27]
	v_mad_u64_u32 v[190:191], s[60:61], v2, s53, v[190:191]
	v_mad_i32_i24 v191, v3, s53, v191
	s_lshl_b32 s28, s59, 1
	v_lshl_add_u64 v[2:3], v[190:191], 0, s[28:29]
	v_mov_b32_e32 v83, v4
	v_lshl_add_u64 v[2:3], v[2:3], 0, v[82:83]
	v_lshl_add_u64 v[190:191], v[2:3], 0, s[30:31]
	v_add_co_u32_e32 v2, vcc, 0x2000, v2
	s_nop 1
	v_addc_co_u32_e32 v3, vcc, 0, v3, vcc
	global_load_dwordx4 v[194:197], v[2:3], off
	s_nop 0
	global_load_dwordx4 v[190:193], v[190:191], off offset:1024
.LBB0_1415:
	s_or_b64 exec, exec, s[50:51]
	v_mov_b32_e32 v202, 0
	v_mov_b32_e32 v203, 0
	v_mov_b32_e32 v204, 0
	v_mov_b32_e32 v205, 0
	v_mov_b32_e32 v198, 0
	v_mov_b32_e32 v199, 0
	v_mov_b32_e32 v200, 0
	v_mov_b32_e32 v201, 0
	s_and_saveexec_b64 s[50:51], s[24:25]
	s_cbranch_execz .LBB0_1417
	v_lshl_add_u64 v[2:3], s[48:49], 0, v[72:73]
	v_mov_b64_e32 v[198:199], s[26:27]
	v_mad_u64_u32 v[198:199], s[48:49], v2, s53, v[198:199]
	v_mad_i32_i24 v199, v3, s53, v199
	s_lshl_b32 s28, s59, 1
	v_lshl_add_u64 v[2:3], v[198:199], 0, s[28:29]
	v_mov_b32_e32 v83, v4
	v_lshl_add_u64 v[2:3], v[2:3], 0, v[82:83]
	v_lshl_add_u64 v[198:199], v[2:3], 0, s[30:31]
	v_add_co_u32_e32 v2, vcc, 0x2000, v2
	s_nop 1
	v_addc_co_u32_e32 v3, vcc, 0, v3, vcc
	global_load_dwordx4 v[202:205], v[2:3], off
	s_nop 0
	global_load_dwordx4 v[198:201], v[198:199], off offset:1024
.LBB0_1417:
	s_or_b64 exec, exec, s[50:51]
	s_waitcnt vmcnt(0)
	ds_write_b128 v92, v[12:15]
	ds_write_b128 v92, v[8:11] offset:36864
	ds_write_b128 v93, v[36:39]
	ds_write_b128 v93, v[32:35] offset:36864
	ds_write_b128 v94, v[194:197]
	ds_write_b128 v94, v[190:193] offset:36864
	ds_write_b128 v95, v[202:205]
	ds_write_b128 v95, v[198:201] offset:36864
	s_and_saveexec_b64 s[48:49], s[0:1]
	v_add_u32_e32 v2, v55, v88
	ds_write_b128 v2, v[100:103] offset:36864
	s_or_b64 exec, exec, s[48:49]
	s_lshl_b32 s28, s58, 3
	s_add_i32 s48, s28, s41
	s_ashr_i32 s49, s48, 31
	s_lshl_b64 s[48:49], s[48:49], 2
	s_add_u32 s48, s44, s48
	s_addc_u32 s49, s45, s49
	s_waitcnt lgkmcnt(0)
	s_barrier
	global_load_dword v2, v4, s[48:49]
	v_and_b32_e32 v5, 64, v96
	s_mul_i32 s50, s46, 0x1400000
	v_xor_b32_e32 v3, 16, v96
	s_mul_hi_i32 s49, s46, 0x1400000
	v_add_u32_e32 v5, 64, v5
	s_add_u32 s50, s50, s38
	v_xor_b32_e32 v6, 32, v96
	v_cmp_lt_i32_e32 vcc, v3, v5
	s_addc_u32 s51, s49, s39
	s_lshl_b64 s[46:47], s[46:47], 24
	v_cndmask_b32_e32 v3, v96, v3, vcc
	v_cmp_lt_i32_e32 vcc, v6, v5
	s_add_u32 s38, s46, s38
	s_addc_u32 s39, s47, s39
	v_cndmask_b32_e32 v5, v96, v6, vcc
	s_mov_b32 s28, 0
	s_movk_i32 s48, 0xffc0
	v_lshlrev_b32_e32 v83, 2, v3
	v_lshlrev_b32_e32 v84, 2, v5
	v_lshl_add_u64 v[50:51], v[78:79], 0, s[50:51]
	v_lshl_add_u64 v[52:53], v[80:81], 0, s[38:39]
	s_mov_b32 s38, 0
	global_load_dwordx4 v[180:183], v[50:51], off offset:-64
	global_load_dwordx4 v[184:187], v[50:51], off
	v_lshl_add_u64 v[50:51], v[50:51], 0, s[34:35]
	s_waitcnt vmcnt(0)
	v_mul_f32_e32 v85, 0x3fb8aa3b, v2
	v_max_f32_e32 v86, 0xff800000, v85
	s_branch .Lattq_entry_B
